# v72 + ssd_s1: C-channel conv raw rows fetched together with the B-channel rows (same rows, +1024 B) instead of in a second exposed round trip
# baseline (speedup 1.0000x reference)
; __device__ __forceinline__ unsigned pk2(float lo, float hi) { f32x2_t v = {lo, hi}; bf16x2_t b = __builtin_convertvector(v, bf16x2_t); return __builtin_bit_cast(unsigned, b); }
; __device__ __forceinline__ float silu_f(float x) { return x * __builtin_amdgcn_rcpf(1.f + __builtin_amdgcn_exp2f(x * -1.4426950408889634f)); }
; __device__ __forceinline__ void conv4x8(const Params& p, int b, int c, int l0, int ch, float (&o)[4][8]) {
;     const bfu* proj = (const bfu*)(p.ws + WS_PROJ);
;     bfu* xbc = (bfu*)(p.ws + WS_XBC);
;     float w0[8], w1[8], w2[8], w3[8], cb[8];
;     ld8f32(p.conv_w + ch, w0); ld8f32(p.conv_w + 2048 + ch, w1); ld8f32(p.conv_w + 4096 + ch, w2); ld8f32(p.conv_w + 6144 + ch, w3); ld8f32(p.conv_b + ch, cb);
;     const int t0 = c * 128 + l0;
;     const size_t rowb = (size_t)b * 4096;
;     float r[7][8];
; #pragma unroll
;     for (int k = 0; k < 7; ++k) {
;         const int t = t0 - 3 + k;
;         ld8f(proj + (rowb + (t < 0 ? 0 : t)) * NPROJ + 4096 + ch, r[k]);
;         if (k < 3) {
; #pragma unroll
;             for (int j = 0; j < 8; ++j) r[k][j] = (t >= 0) ? r[k][j] : 0.f;
;         }
;     }
; #pragma unroll
;     for (int k = 0; k < 4; ++k) {
; #pragma unroll
;         for (int j = 0; j < 8; ++j) o[k][j] = silu_f(cb[j] + w0[j] * r[k][j] + w1[j] * r[k + 1][j] + w2[j] * r[k + 2][j] + w3[j] * r[k + 3][j]);
; __device__ __forceinline__ void ssd_s1_unit(const Params& p, int unit, unsigned char* ldsb) {
;     ...
;         conv4x8(p, b, c, l0, 1024 + g * 128 + cgrp * 8, o);
; #pragma unroll
;         for (int j = 0; j < 8; ++j) { uint2 w; w.x = pk2(o[0][j], o[1][j]); w.y = pk2(o[2][j], o[3][j]); *(uint2*)(BT + (cgrp * 8 + j) * 136 + l0) = w; }
;         conv4x8(p, b, c, l0, 1536 + g * 128 + cgrp * 8, o);
.LBB0_377:
	s_or_b64 exec, exec, s[24:25]
	v_add_u32_e32 v102, s77, v200
	s_ashr_i32 s61, s60, 31
	s_lshl_b64 s[62:63], s[60:61], 12
	v_sub_u32_e64 v80, v102, 3 clamp
	v_lshl_add_u64 v[0:1], s[62:63], 0, v[80:81]
	v_lshl_or_b32 v85, s79, 7, v201
	v_mad_u64_u32 v[2:3], s[24:25], v0, s68, v[82:83]
	v_or_b32_e32 v4, 0x400, v85
	v_mad_i32_i24 v3, v1, s68, v3
	v_lshl_add_u64 v[94:95], v[2:3], 0, s[56:57]
	v_lshlrev_b32_e32 v80, 1, v4
	v_lshl_add_u64 v[0:1], v[94:95], 0, v[80:81]
	s_waitcnt lgkmcnt(0)
	s_barrier
	global_load_dwordx4 v[32:35], v[0:1], off
	global_load_dwordx4 v[212:215], v[0:1], off offset:1024
	v_sub_u32_e64 v0, v102, 2 clamp
	v_mov_b32_e32 v1, v81
	v_lshl_add_u64 v[0:1], s[62:63], 0, v[0:1]
	v_mad_u64_u32 v[2:3], s[24:25], v0, s68, v[82:83]
	v_mad_i32_i24 v3, v1, s68, v3
	v_lshl_add_u64 v[98:99], v[2:3], 0, s[56:57]
	v_lshl_add_u64 v[0:1], v[98:99], 0, v[80:81]
	global_load_dwordx4 v[36:39], v[0:1], off
	global_load_dwordx4 v[216:219], v[0:1], off offset:1024
	v_sub_u32_e64 v0, v102, 1 clamp
	v_mov_b32_e32 v1, v81
	v_lshl_add_u64 v[0:1], s[62:63], 0, v[0:1]
	v_mad_u64_u32 v[2:3], s[24:25], v0, s68, v[82:83]
	v_mad_i32_i24 v3, v1, s68, v3
	v_lshl_add_u64 v[96:97], v[2:3], 0, s[56:57]
	v_mov_b32_e32 v103, v81
	v_lshl_add_u64 v[0:1], v[96:97], 0, v[80:81]
	v_lshl_add_u64 v[60:61], s[62:63], 0, v[102:103]
	global_load_dwordx4 v[40:43], v[0:1], off
	global_load_dwordx4 v[220:223], v[0:1], off offset:1024
	v_mad_u64_u32 v[0:1], s[24:25], v60, s68, v[82:83]
	v_mad_i32_i24 v1, v61, s68, v1
	v_lshl_add_u64 v[100:101], v[0:1], 0, s[56:57]
	v_lshl_add_u64 v[0:1], v[100:101], 0, v[80:81]
	global_load_dwordx4 v[46:49], v[0:1], off
	global_load_dwordx4 v[224:227], v[0:1], off offset:1024
	v_lshlrev_b32_e32 v116, 2, v4
	global_load_dwordx4 v[0:3], v116, s[4:5] offset:16
	global_load_dwordx4 v[12:15], v116, s[4:5]
	global_load_dwordx4 v[4:7], v116, s[50:51] offset:16
	global_load_dwordx4 v[16:19], v116, s[50:51]
	global_load_dwordx4 v[8:11], v116, s[52:53] offset:16
	global_load_dwordx4 v[20:23], v116, s[52:53]
	global_load_dwordx4 v[24:27], v116, s[36:37]
	global_load_dwordx4 v[28:31], v116, s[38:39]
	v_cmp_eq_u32_e64 s[24:25], 0, v102
	v_lshlrev_b64 v[60:61], 12, v[60:61]
	s_mul_hi_i32 s65, s60, 3
	s_mul_i32 s64, s60, 3
	v_cmp_lt_u32_e64 s[28:29], s69, v102
	s_waitcnt vmcnt(11)
	v_lshlrev_b32_e32 v44, 16, v32
	v_and_b32_e32 v32, 0xffff0000, v32
	v_lshlrev_b32_e32 v45, 16, v33
	v_and_b32_e32 v33, 0xffff0000, v33
	v_lshlrev_b32_e32 v51, 16, v34
	v_and_b32_e32 v34, 0xffff0000, v34
	v_lshlrev_b32_e32 v52, 16, v35
	v_and_b32_e32 v35, 0xffff0000, v35
	v_cndmask_b32_e64 v62, v32, 0, s[24:25]
	s_waitcnt vmcnt(10)
	v_lshlrev_b32_e32 v53, 16, v36
	v_and_b32_e32 v36, 0xffff0000, v36
	v_lshlrev_b32_e32 v54, 16, v37
	v_and_b32_e32 v37, 0xffff0000, v37
	v_lshlrev_b32_e32 v55, 16, v38
	v_and_b32_e32 v38, 0xffff0000, v38
	v_lshlrev_b32_e32 v56, 16, v39
	v_and_b32_e32 v39, 0xffff0000, v39
	v_cndmask_b32_e64 v114, v33, 0, s[24:25]
	v_cndmask_b32_e64 v126, v34, 0, s[24:25]
	v_cndmask_b32_e64 v132, v35, 0, s[24:25]
	v_cndmask_b32_e64 v129, v36, 0, s[24:25]
	v_cndmask_b32_e64 v111, v37, 0, s[24:25]
	v_cndmask_b32_e64 v67, v38, 0, s[24:25]
	v_cndmask_b32_e64 v65, v39, 0, s[24:25]
	global_load_dwordx4 v[32:35], v116, s[36:37] offset:16
	global_load_dwordx4 v[36:39], v116, s[38:39] offset:16
	s_waitcnt vmcnt(11)
	v_lshlrev_b32_e32 v57, 16, v40
	v_and_b32_e32 v40, 0xffff0000, v40
	v_lshlrev_b32_e32 v58, 16, v41
	v_and_b32_e32 v41, 0xffff0000, v41
	v_lshlrev_b32_e32 v59, 16, v42
	v_and_b32_e32 v42, 0xffff0000, v42
	v_lshlrev_b32_e32 v63, 16, v43
	v_and_b32_e32 v43, 0xffff0000, v43
	v_cndmask_b32_e64 v75, v40, 0, s[24:25]
	v_cndmask_b32_e64 v73, v41, 0, s[24:25]
	v_cndmask_b32_e64 v71, v42, 0, s[24:25]
	v_cndmask_b32_e64 v69, v43, 0, s[24:25]
	s_waitcnt vmcnt(10)
	v_lshlrev_b32_e32 v40, 16, v48
	v_and_b32_e32 v41, 0xffff0000, v48
	v_lshlrev_b32_e32 v42, 16, v49
	v_and_b32_e32 v43, 0xffff0000, v49
	v_or_b32_e32 v48, 1, v102
	v_mov_b32_e32 v49, v81
	v_lshl_add_u64 v[48:49], s[62:63], 0, v[48:49]
	v_cndmask_b32_e64 v130, v52, 0, s[24:25]
	v_cndmask_b32_e64 v128, v53, 0, s[24:25]
	v_mad_u64_u32 v[52:53], s[26:27], v48, s68, v[82:83]
	v_mad_i32_i24 v53, v49, s68, v53
	v_lshl_add_u64 v[104:105], v[52:53], 0, s[56:57]
	v_or_b32_e32 v52, 2, v102
	v_mov_b32_e32 v53, v81
	v_lshl_add_u64 v[52:53], s[62:63], 0, v[52:53]
	v_cndmask_b32_e64 v110, v54, 0, s[24:25]
	v_cndmask_b32_e64 v66, v55, 0, s[24:25]
	v_mad_u64_u32 v[54:55], s[26:27], v52, s68, v[82:83]
	v_mad_i32_i24 v55, v53, s68, v55
	v_lshl_add_u64 v[106:107], v[54:55], 0, s[56:57]
	v_cndmask_b32_e64 v50, v44, 0, s[24:25]
	v_cndmask_b32_e64 v124, v51, 0, s[24:25]
	v_lshl_add_u64 v[48:49], v[104:105], 0, v[80:81]
	v_lshl_add_u64 v[52:53], v[106:107], 0, v[80:81]
	s_waitcnt vmcnt(3)
	v_mov_b32_e32 v118, v24
	v_mov_b32_e32 v119, v12
	v_mov_b32_e32 v51, v128
	v_cndmask_b32_e64 v74, v57, 0, s[24:25]
	v_cndmask_b32_e64 v72, v58, 0, s[24:25]
	v_cndmask_b32_e64 v70, v59, 0, s[24:25]
	v_cndmask_b32_e64 v64, v56, 0, s[24:25]
	v_lshlrev_b32_e32 v44, 16, v46
	global_load_dwordx4 v[56:59], v[48:49], off
	global_load_dwordx4 v[228:231], v[48:49], off offset:1024
	global_load_dwordx4 v[232:235], v[52:53], off offset:1024
	s_nop 0
	global_load_dwordx4 v[52:55], v[52:53], off
	v_or_b32_e32 v48, 3, v102
	v_mov_b32_e32 v49, v81
	v_pk_mul_f32 v[50:51], v[118:119], v[50:51]
	v_lshl_add_u64 v[48:49], s[62:63], 0, v[48:49]
	v_mov_b32_e32 v138, v16
	v_mov_b32_e32 v139, v20
	v_mov_b32_e32 v142, v74
	v_mov_b32_e32 v143, v44
	s_waitcnt vmcnt(4)
; __device__ __forceinline__ unsigned pk2(float lo, float hi) { f32x2_t v = {lo, hi}; bf16x2_t b = __builtin_convertvector(v, bf16x2_t); return __builtin_bit_cast(unsigned, b); }
; __device__ __forceinline__ float silu_f(float x) { return x * __builtin_amdgcn_rcpf(1.f + __builtin_amdgcn_exp2f(x * -1.4426950408889634f)); }
; __device__ __forceinline__ void conv4x8(const Params& p, int b, int c, int l0, int ch, float (&o)[4][8]) {
;     ...
; #pragma unroll
;     for (int k = 0; k < 4; ++k) {
; #pragma unroll
;         for (int j = 0; j < 8; ++j) o[k][j] = silu_f(cb[j] + w0[j] * r[k][j] + w1[j] * r[k + 1][j] + w2[j] * r[k + 2][j] + w3[j] * r[k + 3][j]);
;         uint4 ov; ov.x = pk2(o[k][0], o[k][1]); ov.y = pk2(o[k][2], o[k][3]); ov.z = pk2(o[k][4], o[k][5]); ov.w = pk2(o[k][6], o[k][7]);
;         *(uint4*)(xbc + (rowb + t0 + k) * 2048 + ch) = ov;
;         if (t0 + k >= 4093) {
;             float* dst = p.out + O_CP + ((size_t)b * 3 + (t0 + k - 4093)) * 2048 + ch;
;             *(float4*)dst = make_float4(r[k + 3][0], r[k + 3][1], r[k + 3][2], r[k + 3][3]); *(float4*)(dst + 4) = make_float4(r[k + 3][4], r[k + 3][5], r[k + 3][6], r[k + 3][7]);
;         }
	v_add_f32_e32 v50, v28, v50
	v_mad_u64_u32 v[108:109], s[26:27], v48, s68, v[82:83]
	v_pk_mul_f32 v[120:121], v[138:139], v[142:143]
	v_add_f32_e32 v50, v50, v51
	v_mad_i32_i24 v109, v49, s68, v109
	v_add_f32_e32 v50, v50, v120
	v_lshl_add_u64 v[108:109], v[108:109], 0, s[56:57]
	v_add_f32_e32 v87, v50, v121
	v_lshl_add_u64 v[48:49], v[108:109], 0, v[80:81]
	v_mul_f32_e32 v50, 0xbfb8aa3b, v87
	v_cndmask_b32_e64 v68, v63, 0, s[24:25]
	v_exp_f32_e32 v63, v50
	global_load_dwordx4 v[236:239], v[48:49], off offset:1024
	global_load_dwordx4 v[48:51], v[48:49], off
	v_mov_b32_e32 v140, v25
	v_mov_b32_e32 v141, v13
	v_add_f32_e32 v89, 1.0, v63
	v_mov_b32_e32 v63, v129
	v_cndmask_b32_e64 v112, v45, 0, s[24:25]
	v_and_b32_e32 v45, 0xffff0000, v46
	v_pk_mul_f32 v[62:63], v[140:141], v[62:63]
	v_mov_b32_e32 v144, v17
	v_mov_b32_e32 v145, v21
	v_mov_b32_e32 v120, v75
	v_mov_b32_e32 v121, v45
	v_add_f32_e32 v62, v29, v62
	v_pk_mul_f32 v[120:121], v[144:145], v[120:121]
	v_add_f32_e32 v62, v62, v63
	v_add_f32_e32 v62, v62, v120
	v_add_f32_e32 v91, v62, v121
	v_mul_f32_e32 v62, 0xbfb8aa3b, v91
	v_mov_b32_e32 v146, v26
	v_mov_b32_e32 v147, v14
	v_mov_b32_e32 v113, v110
	v_lshlrev_b32_e32 v46, 16, v47
	v_exp_f32_e32 v93, v62
	v_pk_mul_f32 v[62:63], v[146:147], v[112:113]
	v_mov_b32_e32 v148, v18
	v_mov_b32_e32 v149, v22
	v_mov_b32_e32 v152, v72
	v_mov_b32_e32 v153, v46
	v_add_f32_e32 v62, v30, v62
	v_pk_mul_f32 v[112:113], v[148:149], v[152:153]
	v_add_f32_e32 v62, v62, v63
	v_add_f32_e32 v62, v62, v112
	v_add_f32_e32 v103, v62, v113
	v_mul_f32_e32 v62, 0xbfb8aa3b, v103
	v_exp_f32_e32 v62, v62
	v_add_f32_e32 v63, 1.0, v93
	v_mov_b32_e32 v150, v27
	v_mov_b32_e32 v151, v15
	v_add_f32_e32 v62, 1.0, v62
	v_mov_b32_e32 v115, v111
	v_and_b32_e32 v47, 0xffff0000, v47
	v_rcp_f32_e32 v93, v63
	v_rcp_f32_e32 v117, v62
	v_pk_mul_f32 v[62:63], v[150:151], v[114:115]
	v_mov_b32_e32 v154, v19
	v_mov_b32_e32 v155, v23
	v_mov_b32_e32 v112, v73
	v_mov_b32_e32 v113, v47
	v_add_f32_e32 v62, v31, v62
	v_pk_mul_f32 v[112:113], v[154:155], v[112:113]
	v_add_f32_e32 v62, v62, v63
	v_add_f32_e32 v62, v62, v112
	v_add_f32_e32 v114, v62, v113
	v_mul_f32_e32 v62, 0xbfb8aa3b, v114
	v_exp_f32_e32 v62, v62
	v_rcp_f32_e32 v89, v89
	s_waitcnt vmcnt(4)
	v_mov_b32_e32 v156, v32
	v_mov_b32_e32 v157, v0
	v_add_f32_e32 v62, 1.0, v62
	v_mov_b32_e32 v125, v66
	v_mul_f32_e32 v122, v87, v89
	v_rcp_f32_e32 v89, v62
	v_pk_mul_f32 v[62:63], v[156:157], v[124:125]
	v_mov_b32_e32 v158, v4
	v_mov_b32_e32 v159, v8
	v_mov_b32_e32 v162, v70
	v_mov_b32_e32 v163, v40
	s_waitcnt vmcnt(3)
	v_add_f32_e32 v62, v36, v62
	v_pk_mul_f32 v[112:113], v[158:159], v[162:163]
	v_add_f32_e32 v62, v62, v63
	v_add_f32_e32 v62, v62, v112
	v_mul_f32_e32 v87, v91, v93
	v_add_f32_e32 v91, v62, v113
	v_mul_f32_e32 v62, 0xbfb8aa3b, v91
	v_mov_b32_e32 v160, v33
	v_mov_b32_e32 v161, v1
	v_mov_b32_e32 v127, v67
	v_exp_f32_e32 v93, v62
	v_pk_mul_f32 v[62:63], v[160:161], v[126:127]
	v_mov_b32_e32 v164, v5
	v_mov_b32_e32 v165, v9
	v_mov_b32_e32 v112, v71
	v_mov_b32_e32 v113, v41
	v_add_f32_e32 v62, v37, v62
	v_pk_mul_f32 v[112:113], v[164:165], v[112:113]
	v_add_f32_e32 v62, v62, v63
	v_add_f32_e32 v62, v62, v112
	v_mul_f32_e32 v120, v103, v117
	v_add_f32_e32 v103, v62, v113
	v_mul_f32_e32 v62, 0xbfb8aa3b, v103
	v_exp_f32_e32 v62, v62
	v_add_f32_e32 v63, 1.0, v93
	v_mov_b32_e32 v166, v34
	v_mov_b32_e32 v167, v2
	v_mov_b32_e32 v131, v64
	v_mul_f32_e32 v89, v114, v89
	v_rcp_f32_e32 v93, v63
	v_add_f32_e32 v114, 1.0, v62
	v_pk_mul_f32 v[62:63], v[166:167], v[130:131]
	v_mov_b32_e32 v168, v6
	v_mov_b32_e32 v169, v10
	v_mov_b32_e32 v182, v68
	v_mov_b32_e32 v183, v42
	v_add_f32_e32 v62, v38, v62
	v_pk_mul_f32 v[112:113], v[168:169], v[182:183]
	v_add_f32_e32 v62, v62, v63
	v_add_f32_e32 v62, v62, v112
	v_add_f32_e32 v115, v62, v113
	v_mul_f32_e32 v62, 0xbfb8aa3b, v115
	v_mov_b32_e32 v170, v35
	v_mov_b32_e32 v171, v3
	v_mov_b32_e32 v133, v65
	v_exp_f32_e32 v117, v62
	v_pk_mul_f32 v[62:63], v[170:171], v[132:133]
	v_mov_b32_e32 v184, v7
	v_mov_b32_e32 v185, v11
	v_mov_b32_e32 v112, v69
	v_mov_b32_e32 v113, v43
	v_add_f32_e32 v62, v39, v62
	v_pk_mul_f32 v[112:113], v[184:185], v[112:113]
	v_add_f32_e32 v62, v62, v63
	v_add_f32_e32 v62, v62, v112
	v_add_f32_e32 v62, v62, v113
	v_mul_f32_e32 v63, 0xbfb8aa3b, v62
	v_exp_f32_e32 v63, v63
	v_add_f32_e32 v113, 1.0, v117
	v_rcp_f32_e32 v112, v114
	v_rcp_f32_e32 v113, v113
	v_add_f32_e32 v63, 1.0, v63
	v_rcp_f32_e32 v63, v63
	v_mul_f32_e32 v126, v91, v93
	v_mul_f32_e32 v93, v103, v112
	v_mul_f32_e32 v124, v115, v113
	v_mul_f32_e32 v91, v62, v63
	v_lshl_add_u64 v[114:115], s[48:49], 0, v[60:61]
	v_cvt_pk_bf16_f32 v130, v122, v87
	v_cvt_pk_bf16_f32 v131, v120, v89
	v_cvt_pk_bf16_f32 v132, v126, v93
	v_cvt_pk_bf16_f32 v133, v124, v91
	v_lshl_add_u64 v[136:137], v[114:115], 0, v[80:81]
	v_add_u32_e32 v112, 0xfffff003, v102
	global_store_dwordx4 v[136:137], v[130:133], off
	s_and_saveexec_b64 s[26:27], s[28:29]
	s_cbranch_execz .LBB0_379
	s_load_dwordx2 s[30:31], s[42:43], 0xb0
	v_mov_b32_e32 v113, v81
	v_lshl_add_u64 v[60:61], s[64:65], 0, v[112:113]
	v_lshlrev_b64 v[60:61], 13, v[60:61]
	v_mov_b32_e32 v117, v81
	s_waitcnt lgkmcnt(0)
	v_lshl_add_u64 v[60:61], s[30:31], 0, v[60:61]
	v_lshl_add_u64 v[60:61], v[60:61], 0, v[116:117]
	v_lshl_add_u64 v[62:63], v[60:61], 0, s[58:59]
	v_add_co_u32_e32 v60, vcc, 0x8300000, v60
	s_nop 1
	v_addc_co_u32_e32 v61, vcc, 0, v61, vcc
	global_store_dwordx4 v[60:61], v[44:47], off
	global_store_dwordx4 v[62:63], v[40:43], off offset:16

; __device__ __forceinline__ unsigned pk2(float lo, float hi) { f32x2_t v = {lo, hi}; bf16x2_t b = __builtin_convertvector(v, bf16x2_t); return __builtin_bit_cast(unsigned, b); }
; __device__ __forceinline__ float silu_f(float x) { return x * __builtin_amdgcn_rcpf(1.f + __builtin_amdgcn_exp2f(x * -1.4426950408889634f)); }
; __device__ __forceinline__ void conv4x8(const Params& p, int b, int c, int l0, int ch, float (&o)[4][8]) {
;     const bfu* proj = (const bfu*)(p.ws + WS_PROJ);
;     bfu* xbc = (bfu*)(p.ws + WS_XBC);
;     float w0[8], w1[8], w2[8], w3[8], cb[8];
;     ld8f32(p.conv_w + ch, w0); ld8f32(p.conv_w + 2048 + ch, w1); ld8f32(p.conv_w + 4096 + ch, w2); ld8f32(p.conv_w + 6144 + ch, w3); ld8f32(p.conv_b + ch, cb);
;     const int t0 = c * 128 + l0;
;     const size_t rowb = (size_t)b * 4096;
;     float r[7][8];
; #pragma unroll
;     for (int k = 0; k < 7; ++k) {
;         const int t = t0 - 3 + k;
;         ld8f(proj + (rowb + (t < 0 ? 0 : t)) * NPROJ + 4096 + ch, r[k]);
;         if (k < 3) {
; #pragma unroll
;             for (int j = 0; j < 8; ++j) r[k][j] = (t >= 0) ? r[k][j] : 0.f;
;         }
;     }
; #pragma unroll
;     for (int k = 0; k < 4; ++k) {
; #pragma unroll
;         for (int j = 0; j < 8; ++j) o[k][j] = silu_f(cb[j] + w0[j] * r[k][j] + w1[j] * r[k + 1][j] + w2[j] * r[k + 2][j] + w3[j] * r[k + 3][j]);
;         uint4 ov; ov.x = pk2(o[k][0], o[k][1]); ov.y = pk2(o[k][2], o[k][3]); ov.z = pk2(o[k][4], o[k][5]); ov.w = pk2(o[k][6], o[k][7]);
;         *(uint4*)(xbc + (rowb + t0 + k) * 2048 + ch) = ov;
;         if (t0 + k >= 4093) {
;             float* dst = p.out + O_CP + ((size_t)b * 3 + (t0 + k - 4093)) * 2048 + ch;
;             *(float4*)dst = make_float4(r[k + 3][0], r[k + 3][1], r[k + 3][2], r[k + 3][3]); *(float4*)(dst + 4) = make_float4(r[k + 3][4], r[k + 3][5], r[k + 3][6], r[k + 3][7]);
;         }
;     }
; __device__ __forceinline__ void ssd_s1_unit(const Params& p, int unit, unsigned char* ldsb) {
;     ...
;         for (int j = 0; j < 8; ++j) { uint2 w; w.x = pk2(o[0][j], o[1][j]); w.y = pk2(o[2][j], o[3][j]); *(uint2*)(BT + (cgrp * 8 + j) * 136 + l0) = w; }
;         conv4x8(p, b, c, l0, 1536 + g * 128 + cgrp * 8, o);
.LBB0_385:
	s_or_b64 exec, exec, s[66:67]
	v_or_b32_e32 v2, 0x600, v85
	v_lshlrev_b32_e32 v80, 1, v2
	v_lshl_add_u64 v[0:1], v[94:95], 0, v[80:81]
	v_mov_b64_e32 v[44:45], v[212:213]
	v_mov_b64_e32 v[46:47], v[214:215]
	v_lshl_add_u64 v[0:1], v[98:99], 0, v[80:81]
	v_mov_b64_e32 v[48:49], v[216:217]
	v_mov_b64_e32 v[50:51], v[218:219]
	v_lshl_add_u64 v[0:1], v[96:97], 0, v[80:81]
	v_mov_b64_e32 v[60:61], v[220:221]
	v_mov_b64_e32 v[62:63], v[222:223]
	v_lshl_add_u64 v[0:1], v[100:101], 0, v[80:81]
	v_mov_b64_e32 v[146:147], v[224:225]
	v_mov_b64_e32 v[148:149], v[226:227]
	v_lshlrev_b32_e32 v94, 2, v2
	global_load_dwordx4 v[0:3], v94, s[4:5] offset:16
	global_load_dwordx4 v[12:15], v94, s[4:5]
	global_load_dwordx4 v[16:19], v94, s[36:37]
	global_load_dwordx4 v[32:35], v94, s[38:39]
	global_load_dwordx4 v[4:7], v94, s[50:51] offset:16
	global_load_dwordx4 v[28:31], v94, s[50:51]
	global_load_dwordx4 v[8:11], v94, s[52:53] offset:16
	global_load_dwordx4 v[36:39], v94, s[52:53]
	v_cvt_pk_bf16_f32 v40, v122, v134
	v_cvt_pk_bf16_f32 v41, v140, v26
	v_cvt_pk_bf16_f32 v26, v87, v135
	v_cvt_pk_bf16_f32 v27, v111, v27
	v_cvt_pk_bf16_f32 v42, v120, v132
	v_cvt_pk_bf16_f32 v43, v138, v24
	v_cvt_pk_bf16_f32 v24, v89, v133
	v_cvt_pk_bf16_f32 v25, v113, v25
	v_cvt_pk_bf16_f32 v52, v126, v130
	v_cvt_pk_bf16_f32 v53, v144, v22
	v_cvt_pk_bf16_f32 v22, v93, v131
	v_cvt_pk_bf16_f32 v23, v123, v23
	v_cvt_pk_bf16_f32 v54, v124, v128
	v_cvt_pk_bf16_f32 v55, v142, v20
	v_cvt_pk_bf16_f32 v20, v91, v129
	v_cvt_pk_bf16_f32 v21, v121, v21
	ds_write2_b64 v206, v[40:41], v[26:27] offset1:34
	ds_write2_b64 v206, v[42:43], v[24:25] offset0:68 offset1:102
	ds_write2_b64 v206, v[52:53], v[22:23] offset0:136 offset1:170
	ds_write2_b64 v206, v[54:55], v[20:21] offset0:204 offset1:238
	global_load_dwordx4 v[20:23], v94, s[36:37] offset:16
	global_load_dwordx4 v[24:27], v94, s[38:39] offset:16
	v_lshl_add_u64 v[40:41], v[104:105], 0, v[80:81]
	v_lshl_add_u64 v[42:43], v[106:107], 0, v[80:81]
	v_lshl_add_u64 v[64:65], v[108:109], 0, v[80:81]
	v_mov_b64_e32 v[56:57], v[228:229]
	v_mov_b64_e32 v[58:59], v[230:231]
	v_mov_b64_e32 v[52:53], v[232:233]
	v_mov_b64_e32 v[54:55], v[234:235]
	s_nop 0
	v_mov_b64_e32 v[40:41], v[236:237]
	v_mov_b64_e32 v[42:43], v[238:239]
	v_lshlrev_b32_e32 v89, 16, v45
	v_and_b32_e32 v91, 0xffff0000, v45
	v_lshlrev_b32_e32 v93, 16, v46
	v_and_b32_e32 v95, 0xffff0000, v46
	v_lshlrev_b32_e32 v68, 16, v60
	v_lshlrev_b32_e32 v96, 16, v63
	v_lshlrev_b32_e32 v103, 16, v47
	v_and_b32_e32 v109, 0xffff0000, v47
	v_lshlrev_b32_e32 v46, 16, v49
	v_and_b32_e32 v47, 0xffff0000, v49
	v_cndmask_b32_e64 v74, v68, 0, s[24:25]
	v_cndmask_b32_e64 v68, v96, 0, s[24:25]
	v_cndmask_b32_e64 v97, v91, 0, s[24:25]
	v_cndmask_b32_e64 v96, v89, 0, s[24:25]
	v_lshlrev_b32_e32 v69, 16, v61
	v_and_b32_e32 v61, 0xffff0000, v61
	v_cndmask_b32_e64 v99, v47, 0, s[24:25]
	v_cndmask_b32_e64 v98, v46, 0, s[24:25]
	s_waitcnt vmcnt(6)
	v_pk_fma_f32 v[96:97], v[18:19], v[96:97], v[34:35]
	v_lshlrev_b32_e32 v85, 16, v44
	v_and_b32_e32 v87, 0xffff0000, v44
	v_lshlrev_b32_e32 v44, 16, v48
	v_and_b32_e32 v45, 0xffff0000, v48
	v_lshlrev_b32_e32 v48, 16, v50
	v_and_b32_e32 v49, 0xffff0000, v50
	v_lshlrev_b32_e32 v50, 16, v51
	v_and_b32_e32 v51, 0xffff0000, v51
	v_cndmask_b32_e64 v73, v61, 0, s[24:25]
	v_cndmask_b32_e64 v72, v69, 0, s[24:25]
	v_pk_fma_f32 v[96:97], v[14:15], v[98:99], v[96:97]
	v_cndmask_b32_e64 v65, v51, 0, s[24:25]
	v_cndmask_b32_e64 v64, v50, 0, s[24:25]
	v_lshlrev_b32_e32 v50, 16, v147
	v_and_b32_e32 v51, 0xffff0000, v147
	s_waitcnt vmcnt(4)
	v_pk_fma_f32 v[96:97], v[30:31], v[72:73], v[96:97]
	v_and_b32_e32 v60, 0xffff0000, v60
	s_waitcnt vmcnt(2)
	v_pk_fma_f32 v[96:97], v[38:39], v[50:51], v[96:97]
	v_cndmask_b32_e64 v75, v60, 0, s[24:25]
	v_cndmask_b32_e64 v60, v85, 0, s[24:25]
	v_mul_f32_e32 v85, 0xbfb8aa3b, v96
	v_cndmask_b32_e64 v61, v87, 0, s[24:25]
	v_exp_f32_e32 v85, v85
	v_mul_f32_e32 v87, 0xbfb8aa3b, v97
	v_cndmask_b32_e64 v107, v95, 0, s[24:25]
	v_cndmask_b32_e64 v106, v93, 0, s[24:25]
	v_lshlrev_b32_e32 v70, 16, v62
	v_and_b32_e32 v62, 0xffff0000, v62
	v_cndmask_b32_e64 v67, v49, 0, s[24:25]
	v_cndmask_b32_e64 v66, v48, 0, s[24:25]
	v_exp_f32_e32 v87, v87
	s_waitcnt vmcnt(0)
	v_pk_fma_f32 v[106:107], v[20:21], v[106:107], v[24:25]
	v_cndmask_b32_e64 v101, v45, 0, s[24:25]
	v_cndmask_b32_e64 v100, v44, 0, s[24:25]
	v_cndmask_b32_e64 v71, v62, 0, s[24:25]
	v_cndmask_b32_e64 v70, v70, 0, s[24:25]
	v_pk_fma_f32 v[60:61], v[16:17], v[60:61], v[32:33]
	v_pk_fma_f32 v[106:107], v[0:1], v[66:67], v[106:107]
	v_lshlrev_b32_e32 v44, 16, v148
	v_and_b32_e32 v45, 0xffff0000, v148
	v_pk_fma_f32 v[60:61], v[12:13], v[100:101], v[60:61]
	v_pk_fma_f32 v[106:107], v[4:5], v[70:71], v[106:107]
	v_lshlrev_b32_e32 v48, 16, v146
	v_and_b32_e32 v49, 0xffff0000, v146
	v_pk_fma_f32 v[60:61], v[28:29], v[74:75], v[60:61]
	v_add_f32_e32 v85, 1.0, v85
	v_pk_fma_f32 v[106:107], v[8:9], v[44:45], v[106:107]
	v_pk_fma_f32 v[60:61], v[36:37], v[48:49], v[60:61]
	v_rcp_f32_e32 v104, v85
	v_add_f32_e32 v85, 1.0, v87
	v_mul_f32_e32 v87, 0xbfb8aa3b, v106
	v_cndmask_b32_e64 v117, v109, 0, s[24:25]
	v_cndmask_b32_e64 v116, v103, 0, s[24:25]
	v_and_b32_e32 v63, 0xffff0000, v63
	v_mul_f32_e32 v47, 0xbfb8aa3b, v60
	v_exp_f32_e32 v87, v87
	v_mul_f32_e32 v89, 0xbfb8aa3b, v107
	v_pk_fma_f32 v[116:117], v[22:23], v[116:117], v[26:27]
	v_cndmask_b32_e64 v69, v63, 0, s[24:25]
	v_exp_f32_e32 v62, v47
	v_mul_f32_e32 v47, 0xbfb8aa3b, v61
	v_exp_f32_e32 v89, v89
	v_pk_fma_f32 v[116:117], v[2:3], v[64:65], v[116:117]
	v_lshlrev_b32_e32 v46, 16, v149
	v_exp_f32_e32 v63, v47
	v_and_b32_e32 v47, 0xffff0000, v149
	v_pk_fma_f32 v[116:117], v[6:7], v[68:69], v[116:117]
	v_rcp_f32_e32 v105, v85
	v_pk_fma_f32 v[116:117], v[10:11], v[46:47], v[116:117]
	v_add_f32_e32 v85, 1.0, v87
	v_mul_f32_e32 v87, 0xbfb8aa3b, v116
	v_rcp_f32_e32 v108, v85
	v_add_f32_e32 v85, 1.0, v89
	v_exp_f32_e32 v87, v87
	v_mul_f32_e32 v89, 0xbfb8aa3b, v117
	v_exp_f32_e32 v89, v89
	v_rcp_f32_e32 v109, v85
	v_add_f32_e32 v85, 1.0, v87
	v_add_f32_e32 v62, 1.0, v62
	v_add_f32_e32 v63, 1.0, v63
	v_rcp_f32_e32 v120, v85
	v_add_f32_e32 v85, 1.0, v89
	v_rcp_f32_e32 v62, v62
	v_rcp_f32_e32 v63, v63
	v_rcp_f32_e32 v121, v85
	v_pk_mul_f32 v[60:61], v[60:61], v[62:63]
	v_pk_mul_f32 v[62:63], v[96:97], v[104:105]
	v_pk_mul_f32 v[96:97], v[106:107], v[108:109]
	v_pk_mul_f32 v[104:105], v[116:117], v[120:121]
	v_cvt_pk_bf16_f32 v60, v60, v61
	v_cvt_pk_bf16_f32 v61, v62, v63
	v_cvt_pk_bf16_f32 v62, v96, v97
	v_cvt_pk_bf16_f32 v63, v104, v105
	v_lshl_add_u64 v[96:97], v[114:115], 0, v[80:81]
	global_store_dwordx4 v[96:97], v[60:63], off
	s_and_saveexec_b64 s[24:25], s[28:29]
	s_cbranch_execz .LBB0_387
; __device__ __forceinline__ void conv4x8(const Params& p, int b, int c, int l0, int ch, float (&o)[4][8]) {
;     ...
;         if (t0 + k >= 4093) {
;             float* dst = p.out + O_CP + ((size_t)b * 3 + (t0 + k - 4093)) * 2048 + ch;
;             *(float4*)dst = make_float4(r[k + 3][0], r[k + 3][1], r[k + 3][2], r[k + 3][3]); *(float4*)(dst + 4) = make_float4(r[k + 3][4], r[k + 3][5], r[k + 3][6], r[k + 3][7]);
;         }
	s_load_dwordx2 s[28:29], s[42:43], 0xb0
	v_mov_b32_e32 v113, v81
	v_lshl_add_u64 v[60:61], s[64:65], 0, v[112:113]
	v_lshlrev_b64 v[60:61], 13, v[60:61]
	v_mov_b32_e32 v95, v81
	s_waitcnt lgkmcnt(0)
	v_lshl_add_u64 v[60:61], s[28:29], 0, v[60:61]
	v_lshl_add_u64 v[60:61], v[60:61], 0, v[94:95]
	v_lshl_add_u64 v[62:63], v[60:61], 0, s[58:59]
	v_add_co_u32_e32 v60, vcc, 0x8300000, v60
	s_nop 1
	v_addc_co_u32_e32 v61, vcc, 0, v61, vcc
	global_store_dwordx4 v[60:61], v[48:51], off
	global_store_dwordx4 v[62:63], v[44:47], off offset:16
